# v22: v21 + P5 hgrn_item packs of the prefetched sub-chunk deferred to the end of the iteration (loads overlap the sub-chunk's compute)
# baseline (speedup 1.0000x reference)
; #define LAS __attribute__((address_space(3)))
; DI unsigned pk2(float lo, float hi) { f32x2 v = {lo, hi}; bfv2 b = __builtin_convertvector(v, bfv2); return __builtin_bit_cast(unsigned, b); }
; DI bf16_t f2bf(float x) { return (bf16_t)(pk2(x, 0.f) & 0xffffu); }
; #define MFMA16(a, b, c) __builtin_amdgcn_mfma_f32_16x16x32_bf16((a), (b), (c), 0, 0, 0)
; template <bool OUT> DI void hgrn_item(LAS unsigned char* lds, bf16_t* proj, float* hst, float* hdv, const float* normw, int item, bool dry) {
;     ...
;                 for (int r = 0; r < 4; ++r) { const int tt = 16 * ti + 4 * rq + r, ss = 16 * sj + e16; Ab[tt * TP + ss] = (sj <= ti && ss <= tt) ? f2bf(a[r]) : (bf16_t)0; }
;             }
; #pragma unroll
;             for (int ti = 0; ti < 4; ++ti) { o[ti] = (f32x4){0.f, 0.f, 0.f, 0.f};
; #pragma unroll
;                 for (int ks = 0; ks < 4; ++ks) { const LAS bf16_t* qp = Qt + (16 * ti + e16) * QP + 32 * ks + 4 * rq; const u32x2 q0 = *(const LAS u32x2*)qp, q1 = *(const LAS u32x2*)(qp + 16);
;                     u32x4 qa = {q0.x, q0.y, q1.x, q1.y};
;                     u32x4 sb; sb.x = pk2(st[2 * ks][0], st[2 * ks][1]); sb.y = pk2(st[2 * ks][2], st[2 * ks][3]); sb.z = pk2(st[2 * ks + 1][0], st[2 * ks + 1][1]); sb.w = pk2(st[2 * ks + 1][2], st[2 * ks + 1][3]);
;                     o[ti] = MFMA16(__builtin_bit_cast(bf16x8, qa), __builtin_bit_cast(bf16x8, sb), o[ti]); } }
;         }
; #pragma unroll
;         for (int dt = 0; dt < 8; ++dt) {
; #pragma unroll
;             for (int ks = 0; ks < 2; ++ks) { const bf16x8 ka = *(const LAS bf16x8*)(KtT + (16 * dt + e16) * TP + 32 * ks + 8 * rq); st[dt] = MFMA16(ka, vfr[ks], st[dt]); }
;             const f32x4 dv = *(const LAS f32x4*)(Dv + 16 * dt + 4 * rq);
;             st[dt] *= dv;
;         }
.LBB0_1170:
	v_or_b32_e32 v56, s14, v104
	v_cmp_gt_u32_e32 vcc, v120, v56
	s_or_b64 s[36:37], s[20:21], vcc
	s_nop 3
	v_cvt_pk_bf16_f32 v50, v50, s0
	v_cndmask_b32_e64 v50, v50, 0, s[36:37]
	v_mad_u64_u32 v[54:55], s[36:37], v56, s39, v[92:93]
	ds_write_b16 v54, v50
	v_or_b32_e32 v50, 1, v56
	v_cmp_gt_u32_e32 vcc, v120, v50
	s_or_b64 s[36:37], s[20:21], vcc
	v_cvt_pk_bf16_f32 v50, v51, s0
	v_cndmask_b32_e64 v50, v50, 0, s[36:37]
	ds_write_b16 v54, v50 offset:144
	v_or_b32_e32 v50, 2, v56
	v_cmp_gt_u32_e32 vcc, v120, v50
	s_or_b64 s[36:37], s[20:21], vcc
	v_cvt_pk_bf16_f32 v50, v52, s0
	v_cndmask_b32_e64 v50, v50, 0, s[36:37]
	ds_write_b16 v54, v50 offset:288
	v_or_b32_e32 v50, 3, v56
	v_cmp_gt_u32_e32 vcc, v120, v50
	s_or_b64 s[36:37], s[20:21], vcc
	v_cvt_pk_bf16_f32 v50, v53, s0
	v_cndmask_b32_e64 v50, v50, 0, s[36:37]
	ds_write_b16 v54, v50 offset:432
	ds_read2_b64 v[50:53], v115 offset1:4
	ds_read2_b64 v[54:57], v115 offset0:8 offset1:12
	s_waitcnt vmcnt(7)
	v_cvt_pk_bf16_f32 v66, v6, v7
	v_cvt_pk_bf16_f32 v67, v8, v9
	s_waitcnt vmcnt(6)
	v_cvt_pk_bf16_f32 v68, v10, v11
	v_cvt_pk_bf16_f32 v69, v12, v13
	s_waitcnt vmcnt(5)
	v_cvt_pk_bf16_f32 v70, v2, v3
	v_cvt_pk_bf16_f32 v71, v4, v5
	s_waitcnt lgkmcnt(1)
	v_mfma_f32_16x16x32_bf16 v[50:53], v[50:53], v[66:69], 0
	s_waitcnt vmcnt(4)
	v_cvt_pk_bf16_f32 v72, v18, v19
	v_cvt_pk_bf16_f32 v73, v20, v21
	s_waitcnt vmcnt(3)
	v_cvt_pk_bf16_f32 v100, v14, v15
	v_cvt_pk_bf16_f32 v101, v16, v17
	s_waitcnt lgkmcnt(0)
	v_mfma_f32_16x16x32_bf16 v[50:53], v[54:57], v[70:73], v[50:53]
	ds_read2_b64 v[54:57], v115 offset0:16 offset1:20
	s_waitcnt vmcnt(2)
	v_cvt_pk_bf16_f32 v102, v26, v27
	v_cvt_pk_bf16_f32 v103, v28, v29
	s_waitcnt vmcnt(1)
	v_cvt_pk_bf16_f32 v144, v22, v23
	v_cvt_pk_bf16_f32 v145, v24, v25
	s_waitcnt lgkmcnt(0)
	v_mfma_f32_16x16x32_bf16 v[50:53], v[54:57], v[100:103], v[50:53]
	ds_read2_b64 v[54:57], v115 offset0:24 offset1:28
	s_waitcnt vmcnt(0)
	v_cvt_pk_bf16_f32 v146, v30, v31
	v_cvt_pk_bf16_f32 v147, v32, v33
	v_add_u32_e32 v62, 0x1000, v115
	ds_read2_b64 v[58:61], v62 offset0:40 offset1:44
	s_waitcnt lgkmcnt(1)
	v_mfma_f32_16x16x32_bf16 v[54:57], v[54:57], v[144:147], v[50:53]
	s_nop 2
	ds_read2_b64 v[50:53], v62 offset0:32 offset1:36
	v_add_u32_e32 v143, 0x2000, v115
	s_waitcnt lgkmcnt(0)
	v_mfma_f32_16x16x32_bf16 v[50:53], v[50:53], v[66:69], 0
	v_mfma_f32_16x16x32_bf16 v[50:53], v[58:61], v[70:73], v[50:53]
	ds_read2_b64 v[58:61], v62 offset0:48 offset1:52
	s_waitcnt lgkmcnt(0)
	v_mfma_f32_16x16x32_bf16 v[50:53], v[58:61], v[100:103], v[50:53]
	ds_read2_b64 v[58:61], v62 offset0:56 offset1:60
	ds_read2_b64 v[62:65], v143 offset0:72 offset1:76
	s_waitcnt lgkmcnt(1)
	v_mfma_f32_16x16x32_bf16 v[58:61], v[58:61], v[144:147], v[50:53]
	s_nop 3
	ds_read2_b64 v[50:53], v143 offset0:64 offset1:68
	s_waitcnt lgkmcnt(0)
	v_mfma_f32_16x16x32_bf16 v[50:53], v[50:53], v[66:69], 0
	v_mfma_f32_16x16x32_bf16 v[50:53], v[62:65], v[70:73], v[50:53]
	ds_read2_b64 v[62:65], v143 offset0:80 offset1:84
	s_waitcnt lgkmcnt(0)
	v_mfma_f32_16x16x32_bf16 v[50:53], v[62:65], v[100:103], v[50:53]
	ds_read2_b64 v[62:65], v143 offset0:88 offset1:92
	v_add_u32_e32 v143, 0x3000, v115
	s_waitcnt lgkmcnt(0)
	v_mfma_f32_16x16x32_bf16 v[62:65], v[62:65], v[144:147], v[50:53]
	s_nop 3
	ds_read2_b64 v[50:53], v143 offset0:96 offset1:100
	s_waitcnt lgkmcnt(0)
	v_mfma_f32_16x16x32_bf16 v[50:53], v[50:53], v[66:69], 0
	ds_read2_b64 v[66:69], v143 offset0:104 offset1:108
	s_waitcnt lgkmcnt(0)
	v_mfma_f32_16x16x32_bf16 v[50:53], v[66:69], v[70:73], v[50:53]
	ds_read2_b64 v[66:69], v143 offset0:112 offset1:116
	s_waitcnt lgkmcnt(0)
	v_mfma_f32_16x16x32_bf16 v[50:53], v[66:69], v[100:103], v[50:53]
	ds_read2_b64 v[66:69], v143 offset0:120 offset1:124
	v_lshl_add_u64 v[102:103], v[98:99], 0, s[34:35]
	v_lshl_add_u64 v[100:101], v[96:97], 0, s[34:35]
	s_waitcnt lgkmcnt(0)
	v_mfma_f32_16x16x32_bf16 v[70:73], v[66:69], v[144:147], v[50:53]
	v_add_u32_e32 v66, v93, v108
	s_nop 1
	ds_read_b128 v[50:53], v66 offset:34816
	v_add_u32_e32 v67, 0x13c00, v93
	s_waitcnt lgkmcnt(0)
	v_mfma_f32_16x16x32_bf16 v[6:9], v[50:53], v[46:49], v[6:9]
	ds_read_b128 v[50:53], v66 offset:34880
	s_add_u32 s34, s34, 0xc8000
	s_addc_u32 s35, s35, 0
	s_waitcnt lgkmcnt(0)
	v_mfma_f32_16x16x32_bf16 v[6:9], v[50:53], v[42:45], v[6:9]
	ds_read_b128 v[50:53], v67
	s_cmp_lg_u32 s34, 0x320000
	s_waitcnt lgkmcnt(0)
	s_nop 4
	v_pk_mul_f32 v[8:9], v[8:9], v[52:53]
	v_pk_mul_f32 v[6:7], v[6:7], v[50:51]
	ds_read_b128 v[50:53], v66 offset:37120
	s_waitcnt lgkmcnt(0)
	v_mfma_f32_16x16x32_bf16 v[10:13], v[50:53], v[46:49], v[10:13]
	ds_read_b128 v[50:53], v66 offset:37184
	s_waitcnt lgkmcnt(0)
	v_mfma_f32_16x16x32_bf16 v[10:13], v[50:53], v[42:45], v[10:13]
	ds_read_b128 v[50:53], v67 offset:64
	s_waitcnt lgkmcnt(0)
	s_nop 5
	v_pk_mul_f32 v[12:13], v[12:13], v[52:53]
	v_pk_mul_f32 v[10:11], v[10:11], v[50:51]
	ds_read_b128 v[50:53], v66 offset:39424
	s_waitcnt lgkmcnt(0)
	v_mfma_f32_16x16x32_bf16 v[2:5], v[50:53], v[46:49], v[2:5]
	ds_read_b128 v[50:53], v66 offset:39488
	s_waitcnt lgkmcnt(0)
	v_mfma_f32_16x16x32_bf16 v[2:5], v[50:53], v[42:45], v[2:5]
	ds_read_b128 v[50:53], v67 offset:128
	s_waitcnt lgkmcnt(0)
	s_nop 5
	v_pk_mul_f32 v[4:5], v[4:5], v[52:53]
	v_pk_mul_f32 v[2:3], v[2:3], v[50:51]
	ds_read_b128 v[50:53], v66 offset:41728
	s_waitcnt lgkmcnt(0)
	v_mfma_f32_16x16x32_bf16 v[18:21], v[50:53], v[46:49], v[18:21]
	ds_read_b128 v[50:53], v66 offset:41792
	s_waitcnt lgkmcnt(0)
	v_mfma_f32_16x16x32_bf16 v[18:21], v[50:53], v[42:45], v[18:21]
	ds_read_b128 v[50:53], v67 offset:192
	s_waitcnt lgkmcnt(0)
; #define LAS __attribute__((address_space(3)))
; template <bool OUT> DI void hgrn_item(LAS unsigned char* lds, bf16_t* proj, float* hst, float* hdv, const float* normw, int item, bool dry) {
;     ...
;         for (int dt = 0; dt < 8; ++dt) {
; #pragma unroll
;             for (int ks = 0; ks < 2; ++ks) { const bf16x8 ka = *(const LAS bf16x8*)(KtT + (16 * dt + e16) * TP + 32 * ks + 8 * rq); st[dt] = MFMA16(ka, vfr[ks], st[dt]); }
;             const f32x4 dv = *(const LAS f32x4*)(Dv + 16 * dt + 4 * rq);
;             st[dt] *= dv;
;         }
;         u32x4 gate8[2];
;         if (OUT) {
; #pragma unroll
;             for (int j = 0; j < 2; ++j) { const int cch = tid + 512 * j; gate8[j] = *(const u32x4*)(proj + (row0 + (cch >> 4)) * NPJ + C_HG + h * 128 + 8 * (cch & 15)); }
;         }
;         __syncthreads();
;         if (OUT) {
; #pragma unroll
;             for (int ti = 0; ti < 4; ++ti)
; #pragma unroll
;                 for (int ks = 0; ks < 2; ++ks) if (2 * ks <= ti) { const bf16x8 aa = *(const LAS bf16x8*)(Ab + (16 * ti + e16) * TP + 32 * ks + 8 * rq); o[ti] = MFMA16(aa, vfr[ks], o[ti]); }
;             LAS float* Ob = (LAS float*)(lds + HOB_OFF);
; #pragma unroll
;             for (int ti = 0; ti < 4; ++ti)
; #pragma unroll
;                 for (int r = 0; r < 4; ++r) Ob[(16 * ti + 4 * rq + r) * OBP + w * 16 + e16] = o[ti][r];
;             __syncthreads();
; #pragma unroll
;             for (int j = 0; j < 2; ++j) { const int cch = tid + 512 * j, tt = cch >> 4, e0 = 8 * (cch & 15);
;                 const f32x4 a0 = *(const LAS f32x4*)(Ob + tt * OBP + e0), a1 = *(const LAS f32x4*)(Ob + tt * OBP + e0 + 4);
;                 float q = (a0[0] * a0[0] + a0[1] * a0[1]) + (a0[2] * a0[2] + a0[3] * a0[3]) + (a1[0] * a1[0] + a1[1] * a1[1]) + (a1[2] * a1[2] + a1[3] * a1[3]);
;                 q += __shfl_xor(q, 1); q += __shfl_xor(q, 2); q += __shfl_xor(q, 4); q += __shfl_xor(q, 8);
;                 const float rs = __builtin_amdgcn_rsqf(q * (1.0f / 128.0f) + 1e-6f);
;                 const f32x4 n0 = *(const f32x4*)(normw + e0), n1 = *(const f32x4*)(normw + e0 + 4); const u32x4 g = gate8[j];
;                 f32x4 y0, y1;
;                 y0[0] = a0[0] * rs * n0[0] * bflo(g.x); y0[1] = a0[1] * rs * n0[1] * bfhi(g.x); y0[2] = a0[2] * rs * n0[2] * bflo(g.y); y0[3] = a0[3] * rs * n0[3] * bfhi(g.y);
	s_nop 5
	v_pk_mul_f32 v[20:21], v[20:21], v[52:53]
	v_pk_mul_f32 v[18:19], v[18:19], v[50:51]
	ds_read_b128 v[50:53], v66 offset:44032
	s_waitcnt lgkmcnt(0)
	v_mfma_f32_16x16x32_bf16 v[14:17], v[50:53], v[46:49], v[14:17]
	ds_read_b128 v[50:53], v66 offset:44096
	s_waitcnt lgkmcnt(0)
	v_mfma_f32_16x16x32_bf16 v[14:17], v[50:53], v[42:45], v[14:17]
	ds_read_b128 v[50:53], v67 offset:256
	s_waitcnt lgkmcnt(0)
	s_nop 5
	v_pk_mul_f32 v[16:17], v[16:17], v[52:53]
	v_pk_mul_f32 v[14:15], v[14:15], v[50:51]
	ds_read_b128 v[50:53], v66 offset:46336
	s_waitcnt lgkmcnt(0)
	v_mfma_f32_16x16x32_bf16 v[26:29], v[50:53], v[46:49], v[26:29]
	ds_read_b128 v[50:53], v66 offset:46400
	s_waitcnt lgkmcnt(0)
	v_mfma_f32_16x16x32_bf16 v[26:29], v[50:53], v[42:45], v[26:29]
	ds_read_b128 v[50:53], v67 offset:320
	s_waitcnt lgkmcnt(0)
	s_nop 5
	v_pk_mul_f32 v[28:29], v[28:29], v[52:53]
	v_pk_mul_f32 v[26:27], v[26:27], v[50:51]
	ds_read_b128 v[50:53], v66 offset:48640
	s_waitcnt lgkmcnt(0)
	v_mfma_f32_16x16x32_bf16 v[22:25], v[50:53], v[46:49], v[22:25]
	ds_read_b128 v[50:53], v66 offset:48704
	s_waitcnt lgkmcnt(0)
	v_mfma_f32_16x16x32_bf16 v[22:25], v[50:53], v[42:45], v[22:25]
	ds_read_b128 v[50:53], v67 offset:384
	s_waitcnt lgkmcnt(0)
	s_nop 5
	v_pk_mul_f32 v[24:25], v[24:25], v[52:53]
	v_pk_mul_f32 v[22:23], v[22:23], v[50:51]
	ds_read_b128 v[50:53], v66 offset:50944
	s_waitcnt lgkmcnt(0)
	v_mfma_f32_16x16x32_bf16 v[30:33], v[50:53], v[46:49], v[30:33]
	ds_read_b128 v[50:53], v66 offset:51008
	s_waitcnt lgkmcnt(0)
	v_mfma_f32_16x16x32_bf16 v[30:33], v[50:53], v[42:45], v[30:33]
	ds_read_b128 v[50:53], v67 offset:448
	s_waitcnt lgkmcnt(0)
	s_nop 5
	v_pk_mul_f32 v[30:31], v[30:31], v[50:51]
	v_add_co_u32_e32 v50, vcc, s47, v102
	v_pk_mul_f32 v[32:33], v[32:33], v[52:53]
	s_nop 0
	v_addc_co_u32_e32 v51, vcc, 0, v103, vcc
	global_load_dwordx4 v[66:69], v[50:51], off offset:512
	v_add_co_u32_e32 v50, vcc, s47, v100
	s_nop 1
	v_addc_co_u32_e32 v51, vcc, 0, v101, vcc
	global_load_dwordx4 v[50:53], v[50:51], off offset:512
	s_barrier
	ds_read_b128 v[144:147], v116
	s_waitcnt lgkmcnt(0)
	v_mfma_f32_16x16x32_bf16 v[54:57], v[144:147], v[46:49], v[54:57]
	ds_read_b128 v[144:147], v116 offset:2304
	s_waitcnt lgkmcnt(0)
	v_mfma_f32_16x16x32_bf16 v[58:61], v[144:147], v[46:49], v[58:61]
	ds_read_b128 v[144:147], v116 offset:4608
	s_waitcnt lgkmcnt(0)
	v_mfma_f32_16x16x32_bf16 v[62:65], v[144:147], v[46:49], v[62:65]
	ds_read_b128 v[144:147], v116 offset:4672
	s_waitcnt lgkmcnt(0)
	v_mfma_f32_16x16x32_bf16 v[62:65], v[144:147], v[42:45], v[62:65]
	ds_read_b128 v[144:147], v116 offset:6912
	s_waitcnt lgkmcnt(0)
	v_mfma_f32_16x16x32_bf16 v[46:49], v[144:147], v[46:49], v[70:73]
	s_nop 2
	ds_read_b128 v[70:73], v116 offset:6976
	ds_write2_b32 v125, v54, v55 offset1:132
	s_waitcnt lgkmcnt(1)
	v_mfma_f32_16x16x32_bf16 v[42:45], v[70:73], v[42:45], v[46:49]
	s_nop 2
	v_add_u32_e32 v46, 0x400, v125
	ds_write2_b32 v46, v56, v57 offset0:8 offset1:140
	v_add_u32_e32 v46, 0x2000, v125
	ds_write2_b32 v46, v58, v59 offset0:64 offset1:196
	v_add_u32_e32 v46, 0x2400, v125
	ds_write2_b32 v46, v60, v61 offset0:72 offset1:204
	v_add_u32_e32 v46, 0x4200, v125
	ds_write2_b32 v46, v62, v63 offset1:132
	v_add_u32_e32 v46, 0x4600, v125
	ds_write2_b32 v46, v64, v65 offset0:8 offset1:140
	v_add_u32_e32 v46, 0x6200, v125
	ds_write2_b32 v46, v42, v43 offset0:64 offset1:196
	v_add_u32_e32 v42, 0x6600, v125
	ds_write2_b32 v42, v44, v45 offset0:72 offset1:204
	s_waitcnt lgkmcnt(0)
	s_barrier
	ds_read_b128 v[42:45], v117
	ds_read_b128 v[46:49], v117 offset:16
	s_waitcnt vmcnt(1)
	v_lshlrev_b32_e32 v64, 16, v68
	v_and_b32_e32 v65, 0xffff0000, v68
	s_waitcnt lgkmcnt(1)
	v_pk_mul_f32 v[54:55], v[44:45], v[44:45]
	v_pk_mul_f32 v[56:57], v[42:43], v[42:43]
	s_nop 0
	v_pk_mov_b32 v[58:59], v[56:57], v[54:55] op_sel:[1,0]
	v_mov_b32_e32 v57, v55
	v_pk_add_f32 v[54:55], v[58:59], v[56:57]
	s_waitcnt lgkmcnt(0)
	v_pk_mul_f32 v[56:57], v[48:49], v[48:49]
	v_pk_mul_f32 v[58:59], v[46:47], v[46:47]
	v_mov_b32_e32 v60, v56
	v_mov_b32_e32 v61, v58
	v_mov_b32_e32 v58, v57
	v_pk_add_f32 v[56:57], v[60:61], v[58:59]
	v_add_f32_e32 v54, v54, v55
	v_add_f32_e32 v54, v54, v57
	v_add_f32_e32 v54, v56, v54
	ds_bpermute_b32 v55, v110, v54
	s_waitcnt lgkmcnt(0)
	v_add_f32_e32 v54, v54, v55
	ds_bpermute_b32 v55, v111, v54
	s_waitcnt lgkmcnt(0)
	v_add_f32_e32 v54, v54, v55
	ds_bpermute_b32 v55, v112, v54
	s_waitcnt lgkmcnt(0)
	v_add_f32_e32 v62, v54, v55
	global_load_dwordx4 v[54:57], v[78:79], off
	global_load_dwordx4 v[58:61], v[78:79], off offset:16
	ds_bpermute_b32 v63, v113, v62
	s_waitcnt lgkmcnt(0)
	v_add_f32_e32 v62, v62, v63
	v_fmamk_f32 v62, v62, 0x3c000000, v118
	v_rsq_f32_e32 v62, v62
	s_nop 0
	v_pk_mul_f32 v[46:47], v[46:47], v[62:63] op_sel_hi:[1,0]
	v_pk_mul_f32 v[48:49], v[48:49], v[62:63] op_sel_hi:[1,0]
	v_pk_mul_f32 v[42:43], v[42:43], v[62:63] op_sel_hi:[1,0]
	v_pk_mul_f32 v[44:45], v[44:45], v[62:63] op_sel_hi:[1,0]
	s_waitcnt vmcnt(1)
	v_pk_mul_f32 v[42:43], v[54:55], v[42:43]
	s_waitcnt vmcnt(0)
	v_pk_mul_f32 v[46:47], v[58:59], v[46:47]
	v_lshlrev_b32_e32 v58, 16, v69
	v_and_b32_e32 v59, 0xffff0000, v69
	v_pk_mul_f32 v[48:49], v[60:61], v[48:49]
	v_lshlrev_b32_e32 v54, 16, v67
	v_pk_mul_f32 v[48:49], v[48:49], v[58:59]
	v_lshlrev_b32_e32 v58, 16, v66
	v_and_b32_e32 v59, 0xffff0000, v66
	v_and_b32_e32 v55, 0xffff0000, v67
	v_pk_mul_f32 v[44:45], v[56:57], v[44:45]
	v_pk_mul_f32 v[46:47], v[46:47], v[64:65]
	v_pk_mul_f32 v[42:43], v[42:43], v[58:59]
	v_pk_mul_f32 v[44:45], v[44:45], v[54:55]
	v_cvt_pk_bf16_f32 v42, v42, v43
	v_cvt_pk_bf16_f32 v43, v44, v45
	v_cvt_pk_bf16_f32 v44, v46, v47
	v_cvt_pk_bf16_f32 v45, v48, v49
	global_store_dwordx4 v[102:103], v[42:45], off offset:1536
	ds_read_b128 v[42:45], v119
	ds_read_b128 v[46:49], v119 offset:16
	v_lshlrev_b32_e32 v64, 16, v52
	v_and_b32_e32 v65, 0xffff0000, v52
	v_lshlrev_b32_e32 v52, 16, v53
	s_waitcnt lgkmcnt(1)
; #define LAS __attribute__((address_space(3)))
; DI float bflo(unsigned w) { return __uint_as_float(w << 16); }
; DI float bfhi(unsigned w) { return __uint_as_float(w & 0xffff0000u); }
; DI u32x4 pack8(f32x4 a, f32x4 b) { u32x4 w; w.x = pk2(a[0], a[1]); w.y = pk2(a[2], a[3]); w.z = pk2(b[0], b[1]); w.w = pk2(b[2], b[3]); return w; }
; template <bool OUT> DI void hgrn_item(LAS unsigned char* lds, bf16_t* proj, float* hst, float* hdv, const float* normw, int item, bool dry) {
;     ...
;         for (int i = 0; i < 8; ++i) { gl[2 * i] = bflo(rg[i]); gl[2 * i + 1] = bfhi(rg[i]); if (OUT) { qv[2 * i] = bflo(rqv[i]); qv[2 * i + 1] = bfhi(rqv[i]); } }
;         *(LAS u32x4*)(VT + d * TP + tq * 16) = (u32x4){rvv[0], rvv[1], rvv[2], rvv[3]};
;         *(LAS u32x4*)(VT + d * TP + tq * 16 + 8) = (u32x4){rvv[4], rvv[5], rvv[6], rvv[7]};
;     ...
;             for (int j = 0; j < 2; ++j) { const int cch = tid + 512 * j, tt = cch >> 4, e0 = 8 * (cch & 15);
;                 const f32x4 a0 = *(const LAS f32x4*)(Ob + tt * OBP + e0), a1 = *(const LAS f32x4*)(Ob + tt * OBP + e0 + 4);
;                 float q = (a0[0] * a0[0] + a0[1] * a0[1]) + (a0[2] * a0[2] + a0[3] * a0[3]) + (a1[0] * a1[0] + a1[1] * a1[1]) + (a1[2] * a1[2] + a1[3] * a1[3]);
;                 q += __shfl_xor(q, 1); q += __shfl_xor(q, 2); q += __shfl_xor(q, 4); q += __shfl_xor(q, 8);
;                 const float rs = __builtin_amdgcn_rsqf(q * (1.0f / 128.0f) + 1e-6f);
;                 const f32x4 n0 = *(const f32x4*)(normw + e0), n1 = *(const f32x4*)(normw + e0 + 4); const u32x4 g = gate8[j];
;                 f32x4 y0, y1;
;                 y0[0] = a0[0] * rs * n0[0] * bflo(g.x); y0[1] = a0[1] * rs * n0[1] * bfhi(g.x); y0[2] = a0[2] * rs * n0[2] * bflo(g.y); y0[3] = a0[3] * rs * n0[3] * bfhi(g.y);
;                 y1[0] = a1[0] * rs * n1[0] * bflo(g.z); y1[1] = a1[1] * rs * n1[1] * bfhi(g.z); y1[2] = a1[2] * rs * n1[2] * bflo(g.w); y1[3] = a1[3] * rs * n1[3] * bfhi(g.w);
;                 if (!dry) *(u32x4*)(proj + (row0 + tt) * NPJ + C_HQ + h * 128 + e0) = pack8(y0, y1); }
	v_pk_mul_f32 v[54:55], v[44:45], v[44:45]
	v_pk_mul_f32 v[56:57], v[42:43], v[42:43]
	v_and_b32_e32 v53, 0xffff0000, v53
	v_pk_mov_b32 v[58:59], v[56:57], v[54:55] op_sel:[1,0]
	v_mov_b32_e32 v57, v55
	v_pk_add_f32 v[54:55], v[58:59], v[56:57]
	s_waitcnt lgkmcnt(0)
	v_pk_mul_f32 v[56:57], v[48:49], v[48:49]
	v_pk_mul_f32 v[58:59], v[46:47], v[46:47]
	v_mov_b32_e32 v60, v56
	v_mov_b32_e32 v61, v58
	v_mov_b32_e32 v58, v57
	v_pk_add_f32 v[56:57], v[60:61], v[58:59]
	v_add_f32_e32 v54, v54, v55
	v_add_f32_e32 v54, v54, v57
	v_add_f32_e32 v54, v56, v54
	ds_bpermute_b32 v55, v110, v54
	s_waitcnt lgkmcnt(0)
	v_add_f32_e32 v54, v54, v55
	ds_bpermute_b32 v55, v111, v54
	s_waitcnt lgkmcnt(0)
	v_add_f32_e32 v54, v54, v55
	ds_bpermute_b32 v55, v112, v54
	s_waitcnt lgkmcnt(0)
	v_add_f32_e32 v62, v54, v55
	global_load_dwordx4 v[54:57], v[78:79], off
	global_load_dwordx4 v[58:61], v[78:79], off offset:16
	ds_bpermute_b32 v63, v113, v62
	s_waitcnt lgkmcnt(0)
	v_add_f32_e32 v62, v62, v63
	v_fmamk_f32 v62, v62, 0x3c000000, v118
	v_rsq_f32_e32 v62, v62
	s_nop 0
	v_pk_mul_f32 v[48:49], v[48:49], v[62:63] op_sel_hi:[1,0]
	v_pk_mul_f32 v[46:47], v[46:47], v[62:63] op_sel_hi:[1,0]
	v_pk_mul_f32 v[42:43], v[42:43], v[62:63] op_sel_hi:[1,0]
	v_pk_mul_f32 v[44:45], v[44:45], v[62:63] op_sel_hi:[1,0]
	s_waitcnt vmcnt(1)
	v_pk_mul_f32 v[42:43], v[54:55], v[42:43]
	s_waitcnt vmcnt(0)
	v_pk_mul_f32 v[48:49], v[60:61], v[48:49]
	v_pk_mul_f32 v[46:47], v[58:59], v[46:47]
	v_pk_mul_f32 v[48:49], v[48:49], v[52:53]
	v_lshlrev_b32_e32 v52, 16, v50
	v_and_b32_e32 v53, 0xffff0000, v50
	v_lshlrev_b32_e32 v50, 16, v51
	v_and_b32_e32 v51, 0xffff0000, v51
	v_pk_mul_f32 v[44:45], v[56:57], v[44:45]
	v_pk_mul_f32 v[46:47], v[46:47], v[64:65]
	v_pk_mul_f32 v[42:43], v[42:43], v[52:53]
	v_pk_mul_f32 v[44:45], v[44:45], v[50:51]
	v_cvt_pk_bf16_f32 v42, v42, v43
	v_cvt_pk_bf16_f32 v43, v44, v45
	v_cvt_pk_bf16_f32 v44, v46, v47
	v_cvt_pk_bf16_f32 v45, v48, v49
	global_store_dwordx4 v[100:101], v[42:45], off offset:1536
	s_waitcnt vmcnt(1)
	v_lshl_or_b32 v129, v185, 16, v184
	v_lshl_or_b32 v127, v190, 16, v191
	v_lshl_or_b32 v131, v192, 16, v188
	v_lshl_or_b32 v128, v194, 16, v189
	v_lshl_or_b32 v133, v196, 16, v195
	v_lshl_or_b32 v135, v203, 16, v202
	v_lshl_or_b32 v134, v214, 16, v215
	v_lshl_or_b32 v34, v187, 16, v186
	v_lshl_or_b32 v35, v199, 16, v193
	v_lshl_or_b32 v36, v200, 16, v197
	v_lshl_or_b32 v130, v198, 16, v201
	v_lshl_or_b32 v37, v205, 16, v204
	v_lshl_or_b32 v132, v206, 16, v207
	v_lshl_or_b32 v137, v209, 16, v208
	v_lshl_or_b32 v38, v211, 16, v210
	v_lshl_or_b32 v139, v216, 16, v212
	v_lshl_or_b32 v136, v218, 16, v213
	v_lshl_or_b32 v141, v220, 16, v219
	v_lshl_or_b32 v39, v223, 16, v217
	v_lshl_or_b32 v40, v224, 16, v221
	v_lshl_or_b32 v138, v222, 16, v225
	v_lshl_or_b32 v142, v227, 16, v226
	v_lshl_or_b32 v41, v229, 16, v228
	v_lshl_or_b32 v140, v230, 16, v231
	v_mov_b32_e32 v46, v127
	v_mov_b32_e32 v47, v128
	v_mov_b32_e32 v49, v130
	v_mov_b32_e32 v51, v132
	v_mov_b32_e32 v52, v134
	v_mov_b32_e32 v53, v136
	v_mov_b32_e32 v54, v138
	v_mov_b32_e32 v48, v140
	v_mov_b32_e32 v42, v129
	v_mov_b32_e32 v43, v131
	v_mov_b32_e32 v44, v133
	v_mov_b32_e32 v45, v135
	v_mov_b32_e32 v50, v137
	v_mov_b32_e32 v55, v139
	v_mov_b32_e32 v56, v141
	v_mov_b32_e32 v57, v142
	s_cbranch_scc0 .LBB0_1168
; #define LAS __attribute__((address_space(3)))
; template <bool OUT> DI void hgrn_item(LAS unsigned char* lds, bf16_t* proj, float* hst, float* hdv, const float* normw, int item, bool dry) {
;     ...
;         *(LAS u32x4*)(VT + d * TP + tq * 16) = (u32x4){rvv[0], rvv[1], rvv[2], rvv[3]};
;         *(LAS u32x4*)(VT + d * TP + tq * 16 + 8) = (u32x4){rvv[4], rvv[5], rvv[6], rvv[7]};
;         if (sc < 3) HG_LOAD(sc + 1);
.LBB0_1171:
	s_cmp_eq_u32 s34, 0x258000
	ds_write_b128 v77, v[34:37] offset:53248
	ds_write_b128 v77, v[38:41] offset:53264
	s_cbranch_scc1 .LBB0_1173
	v_lshl_add_u64 v[34:35], v[94:95], 0, s[34:35]
	v_add_co_u32_e32 v36, vcc, 0xc8000, v34
	s_nop 1
	v_addc_co_u32_e32 v37, vcc, 0, v35, vcc
	v_add_co_u32_e32 v38, vcc, 0xcb000, v34
	s_nop 1
	v_addc_co_u32_e32 v39, vcc, 0, v35, vcc
	v_add_co_u32_e32 v40, vcc, 0xcc000, v34
	s_nop 1
	v_addc_co_u32_e32 v41, vcc, 0, v35, vcc
	v_add_co_u32_e32 v58, vcc, 0xce000, v34
	s_nop 1
	v_addc_co_u32_e32 v59, vcc, 0, v35, vcc
	global_load_ushort v184, v[36:37], off offset:2560
	global_load_ushort v185, v[38:39], off offset:3072
	global_load_ushort v186, v[36:37], off offset:3584
	global_load_ushort v187, v[40:41], off
	global_load_ushort v188, v[58:59], off offset:3584
	global_load_ushort v189, v[58:59], off offset:2560
	global_load_ushort v190, v[38:39], off offset:2048
	global_load_ushort v191, v[36:37], off offset:1536
	v_add_co_u32_e32 v36, vcc, 0xd2000, v34
	v_addc_co_u32_e32 v37, vcc, 0, v35, vcc
	v_add_co_u32_e32 v38, vcc, 0xcf000, v34
	v_addc_co_u32_e32 v39, vcc, 0, v35, vcc
	v_add_co_u32_e32 v40, vcc, 0xd1000, v34
	s_nop 1
	v_addc_co_u32_e32 v41, vcc, 0, v35, vcc
	v_add_co_u32_e32 v58, vcc, 0xd5000, v34
	s_nop 1
	v_addc_co_u32_e32 v59, vcc, 0, v35, vcc
	v_add_co_u32_e32 v60, vcc, 0xd8000, v34
	s_nop 1
	v_addc_co_u32_e32 v61, vcc, 0, v35, vcc
	global_load_ushort v192, v[36:37], off
	global_load_ushort v193, v[38:39], off offset:512
	global_load_ushort v194, v[40:41], off offset:3072
	global_load_ushort v195, v[58:59], off offset:512
	global_load_ushort v196, v[60:61], off offset:1024
	global_load_ushort v197, v[58:59], off offset:1536
	global_load_ushort v198, v[60:61], off
	global_load_ushort v199, v[36:37], off offset:1024
	v_add_co_u32_e32 v36, vcc, 0xd4000, v34
	v_addc_co_u32_e32 v37, vcc, 0, v35, vcc
	v_add_co_u32_e32 v38, vcc, 0xdb000, v34
	v_addc_co_u32_e32 v39, vcc, 0, v35, vcc
	v_add_co_u32_e32 v40, vcc, 0xde000, v34
	v_addc_co_u32_e32 v41, vcc, 0, v35, vcc
	global_load_ushort v200, v[60:61], off offset:2048
	global_load_ushort v201, v[36:37], off offset:3584
	global_load_ushort v202, v[38:39], off offset:1536
	global_load_ushort v203, v[40:41], off offset:2048
	global_load_ushort v204, v[38:39], off offset:2560
	global_load_ushort v205, v[40:41], off offset:3072
	global_load_ushort v206, v[40:41], off offset:1024
	global_load_ushort v207, v[38:39], off offset:512
	v_add_co_u32_e32 v36, vcc, 0xe1000, v34
	v_addc_co_u32_e32 v37, vcc, 0, v35, vcc
	v_add_co_u32_e32 v38, vcc, 0xe4000, v34
	s_nop 1
	v_addc_co_u32_e32 v39, vcc, 0, v35, vcc
	v_add_co_u32_e32 v40, vcc, 0xe5000, v34
	s_nop 1
	v_addc_co_u32_e32 v41, vcc, 0, v35, vcc
	v_add_co_u32_e32 v58, vcc, 0xe7000, v34
	s_nop 1
	v_addc_co_u32_e32 v59, vcc, 0, v35, vcc
	global_load_ushort v208, v[36:37], off offset:2560
	global_load_ushort v209, v[38:39], off offset:3072
	global_load_ushort v210, v[36:37], off offset:3584
	global_load_ushort v211, v[40:41], off
	global_load_ushort v212, v[58:59], off offset:3584
	global_load_ushort v213, v[58:59], off offset:2560
	global_load_ushort v214, v[38:39], off offset:2048
	global_load_ushort v215, v[36:37], off offset:1536
	v_add_co_u32_e32 v36, vcc, 0xeb000, v34
	v_addc_co_u32_e32 v37, vcc, 0, v35, vcc
	v_add_co_u32_e32 v38, vcc, 0xe8000, v34
	s_nop 1
	v_addc_co_u32_e32 v39, vcc, 0, v35, vcc
	v_add_co_u32_e32 v40, vcc, 0xea000, v34
	s_nop 1
	v_addc_co_u32_e32 v41, vcc, 0, v35, vcc
	v_add_co_u32_e32 v58, vcc, 0xee000, v34
	s_nop 1
	v_addc_co_u32_e32 v59, vcc, 0, v35, vcc
	v_add_co_u32_e32 v60, vcc, 0xf1000, v34
	s_nop 1
	v_addc_co_u32_e32 v61, vcc, 0, v35, vcc
	global_load_ushort v216, v[36:37], off
	global_load_ushort v217, v[38:39], off offset:512
	s_nop 0
	global_load_ushort v218, v[40:41], off offset:3072
	s_nop 0
	global_load_ushort v219, v[58:59], off offset:512
	global_load_ushort v220, v[60:61], off offset:1024
	s_nop 0
	global_load_ushort v221, v[58:59], off offset:1536
	s_nop 0
	global_load_ushort v222, v[60:61], off
	global_load_ushort v223, v[36:37], off offset:1024
	v_add_co_u32_e32 v36, vcc, 0xed000, v34
	s_nop 1
	v_addc_co_u32_e32 v37, vcc, 0, v35, vcc
	v_add_co_u32_e32 v38, vcc, 0xf4000, v34
	s_nop 1
	v_addc_co_u32_e32 v39, vcc, 0, v35, vcc
	v_add_co_u32_e32 v34, vcc, 0xf7000, v34
	s_nop 1
	v_addc_co_u32_e32 v35, vcc, 0, v35, vcc
	global_load_ushort v224, v[60:61], off offset:2048
	s_nop 0
	global_load_ushort v225, v[36:37], off offset:3584
	global_load_ushort v226, v[38:39], off offset:1536
	global_load_ushort v227, v[34:35], off offset:2048
	global_load_ushort v228, v[38:39], off offset:2560
	global_load_ushort v229, v[34:35], off offset:3072
	global_load_ushort v230, v[34:35], off offset:1024
	global_load_ushort v231, v[38:39], off offset:512
